# stick-breaking attention: a wave skips QK/weights/PV for key tiles once its running product R=prod(1-beta) is exactly 0 in every lane (remaining tiles contribute exactly 0; bit-identical); on top of t
# speedup vs baseline: 1.0390x; 1.0263x over previous
.LBB0_51:
	v_lshl_add_u64 v[2:3], s[90:91], 0, v[194:195]
	s_mov_b32 s0, 0x22180000
	v_add_co_u32_e32 v4, vcc, s0, v2
	s_mov_b32 s0, 0x221a0000
	s_nop 0
	v_addc_co_u32_e32 v5, vcc, 0, v3, vcc
	v_add_co_u32_e32 v6, vcc, s0, v2
	v_lshl_add_u64 v[10:11], s[90:91], 0, v[192:193]
	s_nop 0
	v_addc_co_u32_e32 v7, vcc, 0, v3, vcc
	s_mov_b32 s0, 0x24100000
	v_add_co_u32_e32 v12, vcc, s0, v10
	s_waitcnt lgkmcnt(0)
	s_nop 0
	v_addc_co_u32_e32 v13, vcc, 0, v11, vcc
	v_add_co_u32_e32 v10, vcc, 0x24200000, v10
	s_barrier
	s_nop 0
	v_addc_co_u32_e32 v11, vcc, 0, v11, vcc
	global_load_dwordx4 v[2:5], v[4:5], off
	s_nop 0
	global_load_dwordx4 v[6:9], v[6:7], off
	s_nop 0
	global_load_dwordx4 v[144:147], v[12:13], off offset:256
	s_nop 0
	global_load_dwordx4 v[10:13], v[10:11], off offset:256
	s_sub_i32 s18, s25, 63
	s_cmp_le_i32 s18, s24
	s_cselect_b64 s[0:1], -1, 0
	s_bitcmp1_b32 s3, 0
	s_cselect_b32 s16, 0x8800, 0
	s_add_i32 s16, s16, 16
	s_cmp_gt_i32 s18, s24
	s_cbranch_scc1 .LBB0_53
	v_cmp_neq_f32_e32 vcc, 0, v190
	s_cbranch_vccnz .Lsb_live
	s_mov_b64 s[0:1], 0
	s_branch .LBB0_53
.Lsb_live:
	v_add3_u32 v1, s16, v199, v150
	ds_read_b128 v[80:83], v1
	ds_read_b128 v[186:189], v1 offset:32
	s_waitcnt lgkmcnt(1)
	v_mfma_f32_32x32x16_bf16 v[96:111], v[80:83], v[140:143], 0
	ds_read_b128 v[80:83], v1 offset:8704
	s_waitcnt lgkmcnt(1)
	v_mfma_f32_32x32x16_bf16 v[96:111], v[186:189], v[136:139], v[96:111]
	ds_read_b128 v[186:189], v1 offset:8736
	s_waitcnt lgkmcnt(1)
	v_mfma_f32_32x32x16_bf16 v[80:95], v[80:83], v[140:143], 0
	s_waitcnt lgkmcnt(0)
	v_mfma_f32_32x32x16_bf16 v[80:95], v[186:189], v[136:139], v[80:95]
	ds_read_b128 v[186:189], v1 offset:64
	s_waitcnt lgkmcnt(0)
	v_mfma_f32_32x32x16_bf16 v[96:111], v[186:189], v[132:135], v[96:111]
	ds_read_b128 v[186:189], v1 offset:8768
	s_waitcnt lgkmcnt(0)
	v_mfma_f32_32x32x16_bf16 v[80:95], v[186:189], v[132:135], v[80:95]
	ds_read_b128 v[186:189], v1 offset:96
	s_waitcnt lgkmcnt(0)
	v_mfma_f32_32x32x16_bf16 v[96:111], v[186:189], v[128:131], v[96:111]
	ds_read_b128 v[186:189], v1 offset:8800
	s_waitcnt lgkmcnt(0)
	v_mfma_f32_32x32x16_bf16 v[80:95], v[186:189], v[128:131], v[80:95]
	ds_read_b128 v[186:189], v1 offset:128
	s_waitcnt lgkmcnt(0)
	v_mfma_f32_32x32x16_bf16 v[96:111], v[186:189], v[124:127], v[96:111]
	ds_read_b128 v[186:189], v1 offset:8832
	s_waitcnt lgkmcnt(0)
	v_mfma_f32_32x32x16_bf16 v[80:95], v[186:189], v[124:127], v[80:95]
	ds_read_b128 v[186:189], v1 offset:160
	s_waitcnt lgkmcnt(0)
	v_mfma_f32_32x32x16_bf16 v[96:111], v[186:189], v[116:119], v[96:111]
	ds_read_b128 v[186:189], v1 offset:8864
	s_waitcnt lgkmcnt(0)
	v_mfma_f32_32x32x16_bf16 v[80:95], v[186:189], v[116:119], v[80:95]
	ds_read_b128 v[186:189], v1 offset:192
	s_waitcnt vmcnt(5) lgkmcnt(0)
	v_mfma_f32_32x32x16_bf16 v[96:111], v[186:189], v[120:123], v[96:111]
	ds_read_b128 v[186:189], v1 offset:8896
	s_waitcnt lgkmcnt(0)
	v_mfma_f32_32x32x16_bf16 v[80:95], v[186:189], v[120:123], v[80:95]
	ds_read_b128 v[186:189], v1 offset:224
	s_waitcnt vmcnt(4) lgkmcnt(0)
	v_mfma_f32_32x32x16_bf16 v[96:111], v[186:189], v[112:115], v[96:111]
	ds_read_b128 v[186:189], v1 offset:8928
	s_waitcnt lgkmcnt(0)
	v_mfma_f32_32x32x16_bf16 v[80:95], v[186:189], v[112:115], v[80:95]

.LBB0_58:
	s_sub_i32 s0, s2, s3
	s_lshl_b32 s2, s0, 6
	s_cmp_le_i32 s2, s24
	s_cselect_b64 s[0:1], -1, 0
	s_cmp_gt_i32 s2, s24
	s_waitcnt lgkmcnt(0)
	s_barrier
	s_cbranch_scc1 .LBB0_60
	v_cmp_neq_f32_e32 vcc, 0, v190
	s_cbranch_vccnz .Lsb_tail_live
	s_mov_b64 s[0:1], 0
	s_branch .LBB0_60
.Lsb_tail_live:
	v_add3_u32 v1, s18, v199, v150
	ds_read_b128 v[2:5], v1
	s_waitcnt lgkmcnt(0)
	v_mfma_f32_32x32x16_bf16 v[96:111], v[2:5], v[140:143], 0
	ds_read_b128 v[2:5], v1 offset:8704
	s_waitcnt lgkmcnt(0)
	v_mfma_f32_32x32x16_bf16 v[80:95], v[2:5], v[140:143], 0
	ds_read_b128 v[2:5], v1 offset:32
	s_waitcnt lgkmcnt(0)
	v_mfma_f32_32x32x16_bf16 v[96:111], v[2:5], v[136:139], v[96:111]
	ds_read_b128 v[2:5], v1 offset:8736
	s_waitcnt lgkmcnt(0)
	v_mfma_f32_32x32x16_bf16 v[80:95], v[2:5], v[136:139], v[80:95]
	ds_read_b128 v[2:5], v1 offset:64
	s_waitcnt lgkmcnt(0)
	v_mfma_f32_32x32x16_bf16 v[96:111], v[2:5], v[132:135], v[96:111]
	ds_read_b128 v[2:5], v1 offset:8768
	s_waitcnt lgkmcnt(0)
	v_mfma_f32_32x32x16_bf16 v[80:95], v[2:5], v[132:135], v[80:95]
	ds_read_b128 v[2:5], v1 offset:96
	s_waitcnt lgkmcnt(0)
	v_mfma_f32_32x32x16_bf16 v[96:111], v[2:5], v[128:131], v[96:111]
	ds_read_b128 v[2:5], v1 offset:8800
	s_waitcnt lgkmcnt(0)
	v_mfma_f32_32x32x16_bf16 v[80:95], v[2:5], v[128:131], v[80:95]
	ds_read_b128 v[2:5], v1 offset:128
	s_waitcnt lgkmcnt(0)
	v_mfma_f32_32x32x16_bf16 v[96:111], v[2:5], v[124:127], v[96:111]
	ds_read_b128 v[2:5], v1 offset:8832
	s_waitcnt lgkmcnt(0)
	v_mfma_f32_32x32x16_bf16 v[80:95], v[2:5], v[124:127], v[80:95]
	ds_read_b128 v[2:5], v1 offset:160
	s_waitcnt lgkmcnt(0)
	v_mfma_f32_32x32x16_bf16 v[96:111], v[2:5], v[116:119], v[96:111]
	ds_read_b128 v[2:5], v1 offset:8864
	s_waitcnt lgkmcnt(0)
	v_mfma_f32_32x32x16_bf16 v[80:95], v[2:5], v[116:119], v[80:95]
	ds_read_b128 v[2:5], v1 offset:192
	s_waitcnt lgkmcnt(0)
	v_mfma_f32_32x32x16_bf16 v[96:111], v[2:5], v[120:123], v[96:111]
	ds_read_b128 v[2:5], v1 offset:8896
	s_waitcnt lgkmcnt(0)
	v_mfma_f32_32x32x16_bf16 v[80:95], v[2:5], v[120:123], v[80:95]
	ds_read_b128 v[2:5], v1 offset:224
	s_waitcnt lgkmcnt(0)
	v_mfma_f32_32x32x16_bf16 v[96:111], v[2:5], v[112:115], v[96:111]
	ds_read_b128 v[2:5], v1 offset:8928
	s_waitcnt lgkmcnt(0)
	v_mfma_f32_32x32x16_bf16 v[80:95], v[2:5], v[112:115], v[80:95]
